# static s_setprio 1 for waves 0-3 of every workgroup for the whole kernel
# baseline (speedup 1.0000x reference)
.LBB0_6:
	v_readlane_b32 s0, v254, 1
	v_readlane_b32 s1, v254, 2
	s_add_u32 s80, s0, 0xf8
	s_addc_u32 s81, s1, 0
	s_cmp_lt_i32 s55, 0
	s_cselect_b64 s[0:1], -1, 0
	v_writelane_b32 v254, s0, 5
	v_lshrrev_b32_e32 v1, 20, v0
	v_lshrrev_b32_e32 v0, 10, v0
	v_writelane_b32 v254, s1, 6
	s_add_u32 s0, s52, 0x200
	s_addc_u32 s1, s53, 0
	v_writelane_b32 v254, s0, 7
	v_or_b32_e32 v0, v0, v1
	s_movk_i32 s97, 0x3ff
	v_writelane_b32 v254, s1, 8
	s_add_u32 s0, s52, 0x1000
	s_addc_u32 s1, s53, 0
	v_writelane_b32 v254, s0, 9
	v_and_or_b32 v0, v0, s97, v156
	v_mov_b32_e32 v145, 0
	v_writelane_b32 v254, s1, 10
	s_add_u32 s0, s52, 0x1100
	s_addc_u32 s1, s53, 0
	v_writelane_b32 v254, s0, 11
	v_mbcnt_lo_u32_b32 v1, -1, 0
	v_mbcnt_hi_u32_b32 v162, -1, v1
	v_writelane_b32 v254, s1, 12
	s_add_u32 s0, s52, 0x1200
	s_addc_u32 s1, s53, 0
	v_writelane_b32 v254, s0, 13
	v_and_b32_e32 v1, 64, v162
	s_movk_i32 s64, 0x1000
	v_writelane_b32 v254, s1, 14
	s_add_u32 s0, s52, 0x1300
	s_addc_u32 s1, s53, 0
	v_writelane_b32 v254, s0, 15
	s_cmp_eq_u32 s4, 15
	s_mov_b32 s93, 0x8000
	v_writelane_b32 v254, s1, 16
	s_cselect_b64 s[0:1], -1, 0
	v_writelane_b32 v254, s0, 17
	s_cmp_eq_u32 s4, 14
	v_mov_b32_e32 v157, 0x260
	v_writelane_b32 v254, s1, 18
	s_cselect_b64 s[0:1], -1, 0
	v_writelane_b32 v254, s0, 19
	s_cmp_eq_u32 s4, 13
	v_mov_b32_e32 v158, 0x358637bd
	v_writelane_b32 v254, s1, 20
	s_cselect_b64 s[0:1], -1, 0
	v_writelane_b32 v254, s0, 21
	s_cmp_eq_u32 s4, 12
	v_mov_b32_e32 v159, 0x3c0881c4
	v_writelane_b32 v254, s1, 22
	s_cselect_b64 s[0:1], -1, 0
	v_writelane_b32 v254, s0, 23
	s_cmp_eq_u32 s4, 11
	v_mov_b32_e32 v160, 0xbab64f3b
	v_writelane_b32 v254, s1, 24
	s_cselect_b64 s[0:1], -1, 0
	v_writelane_b32 v254, s0, 25
	s_cmp_eq_u32 s4, 10
	v_mov_b32_e32 v146, 1.0
	v_writelane_b32 v254, s1, 26
	s_cselect_b64 s[0:1], -1, 0
	v_writelane_b32 v254, s0, 27
	s_cmp_eq_u32 s4, 9
	v_mov_b32_e32 v161, 1
	v_writelane_b32 v254, s1, 28
	s_cselect_b64 s[0:1], -1, 0
	v_writelane_b32 v254, s0, 29
	s_cmp_eq_u32 s4, 8
	v_xor_b32_e32 v163, 16, v162
	v_writelane_b32 v254, s1, 30
	s_cselect_b64 s[0:1], -1, 0
	v_writelane_b32 v254, s0, 31
	s_cmp_eq_u32 s4, 7
	v_add_u32_e32 v164, 64, v1
	v_writelane_b32 v254, s1, 32
	s_cselect_b64 s[0:1], -1, 0
	v_writelane_b32 v254, s0, 33
	s_cmp_eq_u32 s4, 6
	v_xor_b32_e32 v165, 32, v162
	v_writelane_b32 v254, s1, 34
	s_cselect_b64 s[0:1], -1, 0
	v_writelane_b32 v254, s0, 35
	s_cmp_eq_u32 s4, 5
	v_mov_b32_e32 v166, 0x600
	v_writelane_b32 v254, s1, 36
	s_cselect_b64 s[0:1], -1, 0
	v_writelane_b32 v254, s0, 37
	s_cmp_eq_u32 s4, 4
	v_mov_b32_e32 v167, 0x1800000
	v_writelane_b32 v254, s1, 38
	s_cselect_b64 s[0:1], -1, 0
	v_writelane_b32 v254, s0, 39
	s_cmp_eq_u32 s4, 3
	v_mov_b32_e32 v168, 0x80
	v_writelane_b32 v254, s1, 40
	s_cselect_b64 s[0:1], -1, 0
	v_writelane_b32 v254, s0, 41
	s_cmp_eq_u32 s4, 2
	v_mov_b32_e32 v169, 0x7f800000
	v_writelane_b32 v254, s1, 42
	s_cselect_b64 s[0:1], -1, 0
	v_writelane_b32 v254, s0, 43
	s_cmp_eq_u32 s4, 1
	v_not_b32_e32 v170, 63
	v_writelane_b32 v254, s1, 44
	s_cselect_b64 s[0:1], -1, 0
	v_writelane_b32 v254, s0, 45
	s_cmp_eq_u32 s4, 0
	v_not_b32_e32 v171, 31
	v_writelane_b32 v254, s1, 46
	s_cselect_b64 s[0:1], -1, 0
	v_writelane_b32 v254, s0, 47
	v_mov_b32_e32 v172, 0x7fc00000
	s_movk_i32 s82, 0x11ff
	v_writelane_b32 v254, s1, 48
	s_lshl_b32 s0, s4, 8
	s_add_u32 s0, s52, s0
	s_addc_u32 s1, s53, 0
	s_add_u32 s2, s0, 0x1400
	s_addc_u32 s3, s1, 0
	v_writelane_b32 v254, s2, 49
	s_add_u32 s0, s0, 0x2400
	s_addc_u32 s1, s1, 0
	v_writelane_b32 v254, s3, 50
	v_writelane_b32 v254, s0, 51
	s_mov_b32 s83, 0xffac0000
	s_mov_b32 s34, 0xffb80000
	v_writelane_b32 v254, s1, 52
	s_add_u32 s0, s52, 0x3400
	s_addc_u32 s1, s53, 0
	v_writelane_b32 v254, s0, 53
	s_mov_b32 s35, 0xffc40000
	s_mov_b32 s88, 0xffd00000
	v_writelane_b32 v254, s1, 54
	s_add_u32 s0, s52, 0x3500
	s_addc_u32 s1, s53, 0
	v_writelane_b32 v254, s0, 55
	s_add_i32 s62, 0, 0x1c000
	s_mov_b32 s89, 0xffdc0000
	v_writelane_b32 v254, s1, 56
	s_add_i32 s0, 0, 0x4400
	v_writelane_b32 v254, s0, 57
	s_add_i32 s0, 0, 0x25000
	v_writelane_b32 v254, s0, 58
	s_add_i32 s0, 0, 0x25004
	v_writelane_b32 v254, s0, 59
	v_cmp_eq_u32_e64 s[0:1], 0, v0
	s_mov_b32 s65, 0xffe80000
	s_mov_b32 s60, 0xfff40000
	v_writelane_b32 v254, s0, 60
	s_movk_i32 s61, 0x2ff
	s_mov_b32 s85, 0
	v_writelane_b32 v254, s1, 61
	v_writelane_b32 v254, s80, 62
	s_mov_b64 s[86:87], 0x80
	s_mov_b32 s96, 0x3fd744fd
	s_mov_b64 s[6:7], 0xdce0080
	s_mov_b64 s[8:9], 0x1004100
	s_mov_b64 s[10:11], 0xdca0100
	s_mov_b64 s[12:13], 0x1044100
	s_mov_b64 s[14:15], 0xdce0100
	s_mov_b64 s[16:17], 0x1004180
	s_mov_b64 s[18:19], 0xdca0180
	s_mov_b64 s[20:21], 0x1044180
	s_mov_b64 s[22:23], 0x100
	s_mov_b64 s[36:37], 0x1284100
	s_mov_b64 s[78:79], 0x12c4100
	s_mov_b64 s[74:75], 0x1284180
	s_mov_b64 s[38:39], 0x12c4180
	s_mov_b64 s[26:27], 0x600000
	s_mov_b64 s[2:3], 0x1a04100
	s_mov_b64 s[66:67], 0x1a44100
	s_mov_b64 s[68:69], 0x1a04180
	s_mov_b64 s[70:71], 0x1a44180
	v_writelane_b32 v254, s81, 63
	v_readfirstlane_b32 s98, v156
	s_cmpk_lt_u32 s98, 0x100
	s_cbranch_scc0 .Lprio_x
	s_setprio 1
.Lprio_x:
	s_branch .LBB0_10
.LBB0_7:
	s_or_b64 exec, exec, s[24:25]
	s_waitcnt vmcnt(0)
